# g1 forward substitution: f32 MFMA operand reads 4 steps ahead, row update reads batched
# baseline (speedup 1.0000x reference)
; __device__ __forceinline__ void g1_phase(unsigned char* lds, const Params& p, int l, int hf, const int tid) {
;     ...
;                 f32x4 acc0 = (f32x4){0.f, 0.f, 0.f, 0.f}, acc1 = acc0;
;                 const int kq = lane >> 4;
;                 const float* mcol = MsT + a * 16 + r16;
;                 const float* ucol = UW + (wid * 32 + r16);
;                 for (int ks = 0; ks < 4 * a; ++ks) {
;                     const float av = mcol[(4 * ks + kq) * 68];
;                     const float b0 = ucol[(4 * ks + kq) * 256], b1 = ucol[(4 * ks + kq) * 256 + 16];
;                     acc0 = __builtin_amdgcn_mfma_f32_16x16x4f32(av, b0, acc0, 0, 0, 0);
;                     acc1 = __builtin_amdgcn_mfma_f32_16x16x4f32(av, b1, acc1, 0, 0, 0);
;                 }
; #pragma unroll
;                 for (int jj = 0; jj < 4; ++jj) { float* rp = UW + (a * 16 + quad * 4 + jj) * 256 + wid * 32 + r16; rp[0] -= acc0[jj]; rp[16] -= acc1[jj]; }
.LBB0_340:
	s_cmp_eq_u32 s9, 0
	s_cbranch_scc1 .LBB0_344
	v_mov_b32_e32 v0, 0
	v_mov_b32_e32 v9, v8
	v_mov_b32_e32 v10, v170
	v_mov_b32_e32 v1, v0
	v_mov_b32_e32 v2, v0
	v_mov_b32_e32 v3, v0
	s_waitcnt lgkmcnt(0)
	v_mov_b32_e32 v4, v0
	v_mov_b32_e32 v5, v0
	v_mov_b32_e32 v6, v0
	v_mov_b32_e32 v7, v0
	v_add_u32_e32 v26, 0x1000, v10
	v_add_u32_e32 v27, 0x2000, v10
	v_add_u32_e32 v28, 0x3000, v10
	ds_read_b32 v14, v9
	ds_read2_b32 v[18:19], v10 offset1:16
	ds_read_b32 v15, v9 offset:1088
	ds_read2_b32 v[20:21], v26 offset1:16
	ds_read_b32 v16, v9 offset:2176
	ds_read2_b32 v[22:23], v27 offset1:16
	ds_read_b32 v17, v9 offset:3264
	ds_read2_b32 v[24:25], v28 offset1:16
	s_lshr_b32 s6, s8, 2
	s_add_i32 s6, s6, -1
	s_cmp_eq_u32 s6, 0
	s_cbranch_scc1 .Lg1f_tail
.Lg1f_loop:
	v_add_u32_e32 v9, 0x1100, v9
	v_add_u32_e32 v10, 0x4000, v10
	v_add_u32_e32 v26, 0x4000, v26
	v_add_u32_e32 v27, 0x4000, v27
	v_add_u32_e32 v28, 0x4000, v28
	s_waitcnt lgkmcnt(6)
	v_mfma_f32_16x16x4_f32 v[4:7], v14, v18, v[4:7]
	v_mfma_f32_16x16x4_f32 v[0:3], v14, v19, v[0:3]
	ds_read_b32 v14, v9
	ds_read2_b32 v[18:19], v10 offset1:16
	s_waitcnt lgkmcnt(6)
	v_mfma_f32_16x16x4_f32 v[4:7], v15, v20, v[4:7]
	v_mfma_f32_16x16x4_f32 v[0:3], v15, v21, v[0:3]
	ds_read_b32 v15, v9 offset:1088
	ds_read2_b32 v[20:21], v26 offset1:16
	s_waitcnt lgkmcnt(6)
	v_mfma_f32_16x16x4_f32 v[4:7], v16, v22, v[4:7]
	v_mfma_f32_16x16x4_f32 v[0:3], v16, v23, v[0:3]
	ds_read_b32 v16, v9 offset:2176
	ds_read2_b32 v[22:23], v27 offset1:16
	s_waitcnt lgkmcnt(6)
	v_mfma_f32_16x16x4_f32 v[4:7], v17, v24, v[4:7]
	v_mfma_f32_16x16x4_f32 v[0:3], v17, v25, v[0:3]
	ds_read_b32 v17, v9 offset:3264
	ds_read2_b32 v[24:25], v28 offset1:16
	s_add_i32 s6, s6, -1
	s_cmp_eq_u32 s6, 0
	s_cbranch_scc0 .Lg1f_loop
.Lg1f_tail:
	s_waitcnt lgkmcnt(6)
	v_mfma_f32_16x16x4_f32 v[4:7], v14, v18, v[4:7]
	v_mfma_f32_16x16x4_f32 v[0:3], v14, v19, v[0:3]
	s_waitcnt lgkmcnt(4)
	v_mfma_f32_16x16x4_f32 v[4:7], v15, v20, v[4:7]
	v_mfma_f32_16x16x4_f32 v[0:3], v15, v21, v[0:3]
	s_waitcnt lgkmcnt(2)
	v_mfma_f32_16x16x4_f32 v[4:7], v16, v22, v[4:7]
	v_mfma_f32_16x16x4_f32 v[0:3], v16, v23, v[0:3]
	s_waitcnt lgkmcnt(0)
	v_mfma_f32_16x16x4_f32 v[4:7], v17, v24, v[4:7]
	v_mfma_f32_16x16x4_f32 v[0:3], v17, v25, v[0:3]
	s_nop 1
	v_lshlrev_b32_e32 v9, 10, v114
	v_lshl_or_b32 v9, s9, 14, v9
	v_add_u32_e32 v9, v117, v9
	v_add_u32_e32 v12, 0x8800, v9
	v_add_u32_e32 v13, 0x8c00, v9
	v_add_u32_e32 v22, 0x9000, v9
	v_add_u32_e32 v23, 0x9400, v9
	ds_read2_b32 v[14:15], v12 offset1:16
	ds_read2_b32 v[16:17], v13 offset1:16
	ds_read2_b32 v[18:19], v22 offset1:16
	ds_read2_b32 v[20:21], v23 offset1:16
	s_waitcnt lgkmcnt(3)
	v_sub_f32_e32 v14, v14, v4
	v_sub_f32_e32 v15, v15, v0
	ds_write2_b32 v12, v14, v15 offset1:16
	s_waitcnt lgkmcnt(3)
	v_sub_f32_e32 v16, v16, v5
	v_sub_f32_e32 v17, v17, v1
	ds_write2_b32 v13, v16, v17 offset1:16
	s_waitcnt lgkmcnt(3)
	v_sub_f32_e32 v18, v18, v6
	v_sub_f32_e32 v19, v19, v2
	ds_write2_b32 v22, v18, v19 offset1:16
	s_waitcnt lgkmcnt(3)
	v_sub_f32_e32 v20, v20, v7
	v_sub_f32_e32 v21, v21, v3
	ds_write2_b32 v23, v20, v21 offset1:16
	s_waitcnt lgkmcnt(0)
	s_barrier
